# speedup vs baseline: 1.0065x; 1.0065x over previous
; __device__ __forceinline__ void xcd_barrier(const XcdBarrier& b) {
;   asm volatile("s_waitcnt vmcnt(0)" ::: "memory");
;   __syncthreads();
;   if (threadIdx.x == 0) {
;     unsigned* bar = b.bar;
;     __builtin_amdgcn_s_waitcnt(0);
;     unsigned nloc = b.st[0], nx = b.st[1];
;     if (nloc == 0u) { xcd_barrier_complete(bar, b.x, nloc, nx); b.st[0] = nloc; b.st[1] = nx; }
.LBB0_1270:
	s_or_b64 exec, exec, s[0:1]
	s_waitcnt vmcnt(0)
	v_readlane_b32 s98, v250, 11
	s_nop 3
	s_cmp_lg_u32 s98, 0
	s_cbranch_scc1 .LBB0_1321
	s_barrier
	s_and_saveexec_b64 s[0:1], s[96:97]
	v_readlane_b32 s72, v250, 0
	v_readlane_b32 s78, v250, 2
	v_readlane_b32 s90, v250, 4
	v_readlane_b32 s73, v250, 1
	v_readlane_b32 s79, v250, 3
	v_readlane_b32 s91, v250, 5
	s_cbranch_execz .LBB0_811
	s_waitcnt vmcnt(0) expcnt(0) lgkmcnt(0)
	ds_read_b32 v2, v177
	ds_read_b32 v0, v177 offset:4
	s_waitcnt lgkmcnt(1)
	v_cmp_ne_u32_e32 vcc, 0, v2
	s_cbranch_vccnz .LBB0_1286
	s_mov_b32 s11, 1
	s_branch .LBB0_1274
